# relocated final rows (batch b-1 in the in-proj tail of batch b) as a fully unrolled two-deep load pipeline
# baseline (speedup 1.0000x reference)
.LBB0_916:
	s_waitcnt vmcnt(0)
	v_readlane_b32 s50, v255, 28
	v_readlane_b32 s70, v255, 26
	v_readlane_b32 s51, v255, 29
	v_readlane_b32 s48, v255, 30
	v_readlane_b32 s74, v255, 32
	v_readlane_b32 s42, v255, 35
	v_readlane_b32 s71, v255, 27
	v_readlane_b32 s49, v255, 31
	v_readlane_b32 s75, v255, 33
	v_readlane_b32 s51, v255, 34
	v_readlane_b32 s43, v255, 36
	s_movk_i32 s78, 0xf800
	s_barrier
	s_cmp_lt_i32 s92, 12
	s_cbranch_scc1 .Lfr_skip
	v_readlane_b32 s0, v250, 0
	s_nop 3
	s_cmp_lt_u32 s0, 0x80
	s_cbranch_scc1 .Lfr_skip
	v_mbcnt_lo_u32_b32 v0, -1, 0
	v_mbcnt_hi_u32_b32 v0, -1, v0
	v_lshlrev_b32_e32 v2, 4, v0
	v_mov_b32_e32 v3, v64
	v_readlane_b32 s98, v250, 7
	v_readlane_b32 s99, v250, 8
	s_nop 4
	global_load_dwordx4 v[40:43], v2, s[98:99]
	global_load_dwordx4 v[44:47], v2, s[98:99] offset:1024
	global_load_dwordx4 v[48:51], v2, s[98:99] offset:2048
	global_load_dwordx4 v[52:55], v2, s[98:99] offset:3072
	v_readlane_b32 s98, v254, 22
	v_readlane_b32 s99, v254, 23
	s_mov_b32 s3, 0xffc00000
	s_cmp_gt_i32 s92, 22
	s_cselect_b32 s3, 0x3c00000, s3
	s_ashr_i32 s100, s3, 31
	s_add_u32 s98, s98, s3
	s_addc_u32 s99, s99, s100
	v_lshl_add_u64 v[4:5], s[98:99], 0, v[2:3]
	v_readlane_b32 s0, v254, 29
	v_readlane_b32 s1, v254, 30
	v_readlane_b32 s2, v254, 55
	s_nop 1
	s_sub_u32 s0, s0, 0x10000
	s_subb_u32 s1, s1, 0
	s_sub_i32 s2, s2, 0x400
	s_mov_b32 s100, 0x400000
	s_mov_b32 s101, 0
	v_lshl_add_u64 v[104:105], v[4:5], 0, s[100:101]
	s_mov_b32 s100, 0x800000
	global_load_dwordx4 v[24:27], v64, s[0:1] offset:-48
	global_load_dwordx4 v[28:31], v64, s[0:1] offset:-32
	global_load_dwordx4 v[32:35], v64, s[0:1] offset:-16
	global_load_dwordx4 v[36:39], v64, s[0:1]
	global_load_dwordx4 v[6:9], v[4:5], off offset:-2048
	global_load_dwordx4 v[12:15], v[4:5], off offset:-1024
	global_load_dwordx4 v[16:19], v[4:5], off
	global_load_dwordx4 v[20:23], v[4:5], off offset:1024
	s_add_u32 s0, s0, 0x10000
	s_addc_u32 s1, s1, 0
	global_load_dwordx4 v[72:75], v64, s[0:1] offset:-48
	global_load_dwordx4 v[76:79], v64, s[0:1] offset:-32
	global_load_dwordx4 v[80:83], v64, s[0:1] offset:-16
	global_load_dwordx4 v[84:87], v64, s[0:1]
	global_load_dwordx4 v[88:91], v[104:105], off offset:-2048
	global_load_dwordx4 v[92:95], v[104:105], off offset:-1024
	global_load_dwordx4 v[96:99], v[104:105], off
	global_load_dwordx4 v[100:103], v[104:105], off offset:1024
	s_add_u32 s0, s0, 0x10000
	s_addc_u32 s1, s1, 0
	s_waitcnt vmcnt(12)
	v_add_f32_e32 v24, v24, v25
	v_add_f32_e32 v26, v26, v27
	v_add_f32_e32 v28, v28, v29
	v_add_f32_e32 v30, v30, v31
	v_add_f32_e32 v32, v32, v33
	v_add_f32_e32 v34, v34, v35
	v_add_f32_e32 v36, v36, v37
	v_add_f32_e32 v38, v38, v39
	v_add_f32_e32 v24, v24, v26
	v_add_f32_e32 v28, v28, v30
	v_add_f32_e32 v32, v32, v34
	v_add_f32_e32 v36, v36, v38
	v_add_f32_e32 v24, v24, v28
	v_add_f32_e32 v24, v24, v32
	v_add_f32_e32 v24, v24, v36
	v_fmamk_f32 v24, v24, 0x3a800000, v176
	v_rsq_f32_e32 v24, v24
	s_waitcnt vmcnt(8)
	v_pk_mul_f32 v[6:7], v[6:7], v[24:25] op_sel_hi:[1,0]
	v_pk_mul_f32 v[8:9], v[8:9], v[24:25] op_sel_hi:[1,0]
	v_pk_mul_f32 v[12:13], v[12:13], v[24:25] op_sel_hi:[1,0]
	v_pk_mul_f32 v[14:15], v[14:15], v[24:25] op_sel_hi:[1,0]
	v_pk_mul_f32 v[16:17], v[16:17], v[24:25] op_sel_hi:[1,0]
	v_pk_mul_f32 v[18:19], v[18:19], v[24:25] op_sel_hi:[1,0]
	v_pk_mul_f32 v[20:21], v[20:21], v[24:25] op_sel_hi:[1,0]
	v_pk_mul_f32 v[22:23], v[22:23], v[24:25] op_sel_hi:[1,0]
	v_pk_mul_f32 v[6:7], v[6:7], v[40:41]
	v_pk_mul_f32 v[8:9], v[8:9], v[42:43]
	v_pk_mul_f32 v[12:13], v[12:13], v[44:45]
	v_pk_mul_f32 v[14:15], v[14:15], v[46:47]
	v_pk_mul_f32 v[16:17], v[16:17], v[48:49]
	v_pk_mul_f32 v[18:19], v[18:19], v[50:51]
	v_pk_mul_f32 v[20:21], v[20:21], v[52:53]
	v_pk_mul_f32 v[22:23], v[22:23], v[54:55]
	global_store_dwordx4 v[4:5], v[6:9], off offset:-2048
	global_store_dwordx4 v[4:5], v[12:15], off offset:-1024
	global_store_dwordx4 v[4:5], v[16:19], off
	global_store_dwordx4 v[4:5], v[20:23], off offset:1024
	v_lshl_add_u64 v[4:5], v[4:5], 0, s[100:101]
	global_load_dwordx4 v[24:27], v64, s[0:1] offset:-48
	global_load_dwordx4 v[28:31], v64, s[0:1] offset:-32
	global_load_dwordx4 v[32:35], v64, s[0:1] offset:-16
	global_load_dwordx4 v[36:39], v64, s[0:1]
	global_load_dwordx4 v[6:9], v[4:5], off offset:-2048
	global_load_dwordx4 v[12:15], v[4:5], off offset:-1024
	global_load_dwordx4 v[16:19], v[4:5], off
	global_load_dwordx4 v[20:23], v[4:5], off offset:1024
	s_add_u32 s0, s0, 0x10000
	s_addc_u32 s1, s1, 0
	s_waitcnt vmcnt(12)
	v_add_f32_e32 v72, v72, v73
	v_add_f32_e32 v74, v74, v75
	v_add_f32_e32 v76, v76, v77
	v_add_f32_e32 v78, v78, v79
	v_add_f32_e32 v80, v80, v81
	v_add_f32_e32 v82, v82, v83
	v_add_f32_e32 v84, v84, v85
	v_add_f32_e32 v86, v86, v87
	v_add_f32_e32 v72, v72, v74
	v_add_f32_e32 v76, v76, v78
	v_add_f32_e32 v80, v80, v82
	v_add_f32_e32 v84, v84, v86
	v_add_f32_e32 v72, v72, v76
	v_add_f32_e32 v72, v72, v80
	v_add_f32_e32 v72, v72, v84
	v_fmamk_f32 v72, v72, 0x3a800000, v176
	v_rsq_f32_e32 v72, v72
	s_waitcnt vmcnt(8)
	v_pk_mul_f32 v[88:89], v[88:89], v[72:73] op_sel_hi:[1,0]
	v_pk_mul_f32 v[90:91], v[90:91], v[72:73] op_sel_hi:[1,0]
	v_pk_mul_f32 v[92:93], v[92:93], v[72:73] op_sel_hi:[1,0]
	v_pk_mul_f32 v[94:95], v[94:95], v[72:73] op_sel_hi:[1,0]
	v_pk_mul_f32 v[96:97], v[96:97], v[72:73] op_sel_hi:[1,0]
	v_pk_mul_f32 v[98:99], v[98:99], v[72:73] op_sel_hi:[1,0]
	v_pk_mul_f32 v[100:101], v[100:101], v[72:73] op_sel_hi:[1,0]
	v_pk_mul_f32 v[102:103], v[102:103], v[72:73] op_sel_hi:[1,0]
	v_pk_mul_f32 v[88:89], v[88:89], v[40:41]
	v_pk_mul_f32 v[90:91], v[90:91], v[42:43]
	v_pk_mul_f32 v[92:93], v[92:93], v[44:45]
	v_pk_mul_f32 v[94:95], v[94:95], v[46:47]
	v_pk_mul_f32 v[96:97], v[96:97], v[48:49]
	v_pk_mul_f32 v[98:99], v[98:99], v[50:51]
	v_pk_mul_f32 v[100:101], v[100:101], v[52:53]
	v_pk_mul_f32 v[102:103], v[102:103], v[54:55]
	global_store_dwordx4 v[104:105], v[88:91], off offset:-2048
	global_store_dwordx4 v[104:105], v[92:95], off offset:-1024
	global_store_dwordx4 v[104:105], v[96:99], off
	global_store_dwordx4 v[104:105], v[100:103], off offset:1024
	v_lshl_add_u64 v[104:105], v[104:105], 0, s[100:101]
	global_load_dwordx4 v[72:75], v64, s[0:1] offset:-48
	global_load_dwordx4 v[76:79], v64, s[0:1] offset:-32
	global_load_dwordx4 v[80:83], v64, s[0:1] offset:-16
	global_load_dwordx4 v[84:87], v64, s[0:1]
	global_load_dwordx4 v[88:91], v[104:105], off offset:-2048
	global_load_dwordx4 v[92:95], v[104:105], off offset:-1024
	global_load_dwordx4 v[96:99], v[104:105], off
	global_load_dwordx4 v[100:103], v[104:105], off offset:1024
	s_add_u32 s0, s0, 0x10000
	s_addc_u32 s1, s1, 0
	s_waitcnt vmcnt(12)
	v_add_f32_e32 v24, v24, v25
	v_add_f32_e32 v26, v26, v27
	v_add_f32_e32 v28, v28, v29
	v_add_f32_e32 v30, v30, v31
	v_add_f32_e32 v32, v32, v33
	v_add_f32_e32 v34, v34, v35
	v_add_f32_e32 v36, v36, v37
	v_add_f32_e32 v38, v38, v39
	v_add_f32_e32 v24, v24, v26
	v_add_f32_e32 v28, v28, v30
	v_add_f32_e32 v32, v32, v34
	v_add_f32_e32 v36, v36, v38
	v_add_f32_e32 v24, v24, v28
	v_add_f32_e32 v24, v24, v32
	v_add_f32_e32 v24, v24, v36
	v_fmamk_f32 v24, v24, 0x3a800000, v176
	v_rsq_f32_e32 v24, v24
	s_waitcnt vmcnt(8)
	v_pk_mul_f32 v[6:7], v[6:7], v[24:25] op_sel_hi:[1,0]
	v_pk_mul_f32 v[8:9], v[8:9], v[24:25] op_sel_hi:[1,0]
	v_pk_mul_f32 v[12:13], v[12:13], v[24:25] op_sel_hi:[1,0]
	v_pk_mul_f32 v[14:15], v[14:15], v[24:25] op_sel_hi:[1,0]
	v_pk_mul_f32 v[16:17], v[16:17], v[24:25] op_sel_hi:[1,0]
	v_pk_mul_f32 v[18:19], v[18:19], v[24:25] op_sel_hi:[1,0]
	v_pk_mul_f32 v[20:21], v[20:21], v[24:25] op_sel_hi:[1,0]
	v_pk_mul_f32 v[22:23], v[22:23], v[24:25] op_sel_hi:[1,0]
	v_pk_mul_f32 v[6:7], v[6:7], v[40:41]
	v_pk_mul_f32 v[8:9], v[8:9], v[42:43]
	v_pk_mul_f32 v[12:13], v[12:13], v[44:45]
	v_pk_mul_f32 v[14:15], v[14:15], v[46:47]
	v_pk_mul_f32 v[16:17], v[16:17], v[48:49]
	v_pk_mul_f32 v[18:19], v[18:19], v[50:51]
	v_pk_mul_f32 v[20:21], v[20:21], v[52:53]
	v_pk_mul_f32 v[22:23], v[22:23], v[54:55]
	global_store_dwordx4 v[4:5], v[6:9], off offset:-2048
	global_store_dwordx4 v[4:5], v[12:15], off offset:-1024
	global_store_dwordx4 v[4:5], v[16:19], off
	global_store_dwordx4 v[4:5], v[20:23], off offset:1024
	v_lshl_add_u64 v[4:5], v[4:5], 0, s[100:101]
	global_load_dwordx4 v[24:27], v64, s[0:1] offset:-48
	global_load_dwordx4 v[28:31], v64, s[0:1] offset:-32
	global_load_dwordx4 v[32:35], v64, s[0:1] offset:-16
	global_load_dwordx4 v[36:39], v64, s[0:1]
	global_load_dwordx4 v[6:9], v[4:5], off offset:-2048
	global_load_dwordx4 v[12:15], v[4:5], off offset:-1024
	global_load_dwordx4 v[16:19], v[4:5], off
	global_load_dwordx4 v[20:23], v[4:5], off offset:1024
	s_add_u32 s0, s0, 0x10000
	s_addc_u32 s1, s1, 0
	s_waitcnt vmcnt(12)
	v_add_f32_e32 v72, v72, v73
	v_add_f32_e32 v74, v74, v75
	v_add_f32_e32 v76, v76, v77
	v_add_f32_e32 v78, v78, v79
	v_add_f32_e32 v80, v80, v81
	v_add_f32_e32 v82, v82, v83
	v_add_f32_e32 v84, v84, v85
	v_add_f32_e32 v86, v86, v87
	v_add_f32_e32 v72, v72, v74
	v_add_f32_e32 v76, v76, v78
	v_add_f32_e32 v80, v80, v82
	v_add_f32_e32 v84, v84, v86
	v_add_f32_e32 v72, v72, v76
	v_add_f32_e32 v72, v72, v80
	v_add_f32_e32 v72, v72, v84
	v_fmamk_f32 v72, v72, 0x3a800000, v176
	v_rsq_f32_e32 v72, v72
	s_waitcnt vmcnt(8)
	v_pk_mul_f32 v[88:89], v[88:89], v[72:73] op_sel_hi:[1,0]
	v_pk_mul_f32 v[90:91], v[90:91], v[72:73] op_sel_hi:[1,0]
	v_pk_mul_f32 v[92:93], v[92:93], v[72:73] op_sel_hi:[1,0]
	v_pk_mul_f32 v[94:95], v[94:95], v[72:73] op_sel_hi:[1,0]
	v_pk_mul_f32 v[96:97], v[96:97], v[72:73] op_sel_hi:[1,0]
	v_pk_mul_f32 v[98:99], v[98:99], v[72:73] op_sel_hi:[1,0]
	v_pk_mul_f32 v[100:101], v[100:101], v[72:73] op_sel_hi:[1,0]
	v_pk_mul_f32 v[102:103], v[102:103], v[72:73] op_sel_hi:[1,0]
	v_pk_mul_f32 v[88:89], v[88:89], v[40:41]
	v_pk_mul_f32 v[90:91], v[90:91], v[42:43]
	v_pk_mul_f32 v[92:93], v[92:93], v[44:45]
	v_pk_mul_f32 v[94:95], v[94:95], v[46:47]
	v_pk_mul_f32 v[96:97], v[96:97], v[48:49]
	v_pk_mul_f32 v[98:99], v[98:99], v[50:51]
	v_pk_mul_f32 v[100:101], v[100:101], v[52:53]
	v_pk_mul_f32 v[102:103], v[102:103], v[54:55]
	global_store_dwordx4 v[104:105], v[88:91], off offset:-2048
	global_store_dwordx4 v[104:105], v[92:95], off offset:-1024
	global_store_dwordx4 v[104:105], v[96:99], off
	global_store_dwordx4 v[104:105], v[100:103], off offset:1024
	v_lshl_add_u64 v[104:105], v[104:105], 0, s[100:101]
	global_load_dwordx4 v[72:75], v64, s[0:1] offset:-48
	global_load_dwordx4 v[76:79], v64, s[0:1] offset:-32
	global_load_dwordx4 v[80:83], v64, s[0:1] offset:-16
	global_load_dwordx4 v[84:87], v64, s[0:1]
	global_load_dwordx4 v[88:91], v[104:105], off offset:-2048
	global_load_dwordx4 v[92:95], v[104:105], off offset:-1024
	global_load_dwordx4 v[96:99], v[104:105], off
	global_load_dwordx4 v[100:103], v[104:105], off offset:1024
	s_add_u32 s0, s0, 0x10000
	s_addc_u32 s1, s1, 0
	s_waitcnt vmcnt(12)
	v_add_f32_e32 v24, v24, v25
	v_add_f32_e32 v26, v26, v27
	v_add_f32_e32 v28, v28, v29
	v_add_f32_e32 v30, v30, v31
	v_add_f32_e32 v32, v32, v33
	v_add_f32_e32 v34, v34, v35
	v_add_f32_e32 v36, v36, v37
	v_add_f32_e32 v38, v38, v39
	v_add_f32_e32 v24, v24, v26
	v_add_f32_e32 v28, v28, v30
	v_add_f32_e32 v32, v32, v34
	v_add_f32_e32 v36, v36, v38
	v_add_f32_e32 v24, v24, v28
	v_add_f32_e32 v24, v24, v32
	v_add_f32_e32 v24, v24, v36
	v_fmamk_f32 v24, v24, 0x3a800000, v176
	v_rsq_f32_e32 v24, v24
	s_waitcnt vmcnt(8)
	v_pk_mul_f32 v[6:7], v[6:7], v[24:25] op_sel_hi:[1,0]
	v_pk_mul_f32 v[8:9], v[8:9], v[24:25] op_sel_hi:[1,0]
	v_pk_mul_f32 v[12:13], v[12:13], v[24:25] op_sel_hi:[1,0]
	v_pk_mul_f32 v[14:15], v[14:15], v[24:25] op_sel_hi:[1,0]
	v_pk_mul_f32 v[16:17], v[16:17], v[24:25] op_sel_hi:[1,0]
	v_pk_mul_f32 v[18:19], v[18:19], v[24:25] op_sel_hi:[1,0]
	v_pk_mul_f32 v[20:21], v[20:21], v[24:25] op_sel_hi:[1,0]
	v_pk_mul_f32 v[22:23], v[22:23], v[24:25] op_sel_hi:[1,0]
	v_pk_mul_f32 v[6:7], v[6:7], v[40:41]
	v_pk_mul_f32 v[8:9], v[8:9], v[42:43]
	v_pk_mul_f32 v[12:13], v[12:13], v[44:45]
	v_pk_mul_f32 v[14:15], v[14:15], v[46:47]
	v_pk_mul_f32 v[16:17], v[16:17], v[48:49]
	v_pk_mul_f32 v[18:19], v[18:19], v[50:51]
	v_pk_mul_f32 v[20:21], v[20:21], v[52:53]
	v_pk_mul_f32 v[22:23], v[22:23], v[54:55]
	global_store_dwordx4 v[4:5], v[6:9], off offset:-2048
	global_store_dwordx4 v[4:5], v[12:15], off offset:-1024
	global_store_dwordx4 v[4:5], v[16:19], off
	global_store_dwordx4 v[4:5], v[20:23], off offset:1024
	v_lshl_add_u64 v[4:5], v[4:5], 0, s[100:101]
	global_load_dwordx4 v[24:27], v64, s[0:1] offset:-48
	global_load_dwordx4 v[28:31], v64, s[0:1] offset:-32
	global_load_dwordx4 v[32:35], v64, s[0:1] offset:-16
	global_load_dwordx4 v[36:39], v64, s[0:1]
	global_load_dwordx4 v[6:9], v[4:5], off offset:-2048
	global_load_dwordx4 v[12:15], v[4:5], off offset:-1024
	global_load_dwordx4 v[16:19], v[4:5], off
	global_load_dwordx4 v[20:23], v[4:5], off offset:1024
	s_add_u32 s0, s0, 0x10000
	s_addc_u32 s1, s1, 0
	s_waitcnt vmcnt(12)
	v_add_f32_e32 v72, v72, v73
	v_add_f32_e32 v74, v74, v75
	v_add_f32_e32 v76, v76, v77
	v_add_f32_e32 v78, v78, v79
	v_add_f32_e32 v80, v80, v81
	v_add_f32_e32 v82, v82, v83
	v_add_f32_e32 v84, v84, v85
	v_add_f32_e32 v86, v86, v87
	v_add_f32_e32 v72, v72, v74
	v_add_f32_e32 v76, v76, v78
	v_add_f32_e32 v80, v80, v82
	v_add_f32_e32 v84, v84, v86
	v_add_f32_e32 v72, v72, v76
	v_add_f32_e32 v72, v72, v80
	v_add_f32_e32 v72, v72, v84
	v_fmamk_f32 v72, v72, 0x3a800000, v176
	v_rsq_f32_e32 v72, v72
	s_waitcnt vmcnt(8)
	v_pk_mul_f32 v[88:89], v[88:89], v[72:73] op_sel_hi:[1,0]
	v_pk_mul_f32 v[90:91], v[90:91], v[72:73] op_sel_hi:[1,0]
	v_pk_mul_f32 v[92:93], v[92:93], v[72:73] op_sel_hi:[1,0]
	v_pk_mul_f32 v[94:95], v[94:95], v[72:73] op_sel_hi:[1,0]
	v_pk_mul_f32 v[96:97], v[96:97], v[72:73] op_sel_hi:[1,0]
	v_pk_mul_f32 v[98:99], v[98:99], v[72:73] op_sel_hi:[1,0]
	v_pk_mul_f32 v[100:101], v[100:101], v[72:73] op_sel_hi:[1,0]
	v_pk_mul_f32 v[102:103], v[102:103], v[72:73] op_sel_hi:[1,0]
	v_pk_mul_f32 v[88:89], v[88:89], v[40:41]
	v_pk_mul_f32 v[90:91], v[90:91], v[42:43]
	v_pk_mul_f32 v[92:93], v[92:93], v[44:45]
	v_pk_mul_f32 v[94:95], v[94:95], v[46:47]
	v_pk_mul_f32 v[96:97], v[96:97], v[48:49]
	v_pk_mul_f32 v[98:99], v[98:99], v[50:51]
	v_pk_mul_f32 v[100:101], v[100:101], v[52:53]
	v_pk_mul_f32 v[102:103], v[102:103], v[54:55]
	global_store_dwordx4 v[104:105], v[88:91], off offset:-2048
	global_store_dwordx4 v[104:105], v[92:95], off offset:-1024
	global_store_dwordx4 v[104:105], v[96:99], off
	global_store_dwordx4 v[104:105], v[100:103], off offset:1024
	v_lshl_add_u64 v[104:105], v[104:105], 0, s[100:101]
	global_load_dwordx4 v[72:75], v64, s[0:1] offset:-48
	global_load_dwordx4 v[76:79], v64, s[0:1] offset:-32
	global_load_dwordx4 v[80:83], v64, s[0:1] offset:-16
	global_load_dwordx4 v[84:87], v64, s[0:1]
	global_load_dwordx4 v[88:91], v[104:105], off offset:-2048
	global_load_dwordx4 v[92:95], v[104:105], off offset:-1024
	global_load_dwordx4 v[96:99], v[104:105], off
	global_load_dwordx4 v[100:103], v[104:105], off offset:1024
	s_add_u32 s0, s0, 0x10000
	s_addc_u32 s1, s1, 0
	s_waitcnt vmcnt(12)
	v_add_f32_e32 v24, v24, v25
	v_add_f32_e32 v26, v26, v27
	v_add_f32_e32 v28, v28, v29
	v_add_f32_e32 v30, v30, v31
	v_add_f32_e32 v32, v32, v33
	v_add_f32_e32 v34, v34, v35
	v_add_f32_e32 v36, v36, v37
	v_add_f32_e32 v38, v38, v39
	v_add_f32_e32 v24, v24, v26
	v_add_f32_e32 v28, v28, v30
	v_add_f32_e32 v32, v32, v34
	v_add_f32_e32 v36, v36, v38
	v_add_f32_e32 v24, v24, v28
	v_add_f32_e32 v24, v24, v32
	v_add_f32_e32 v24, v24, v36
	v_fmamk_f32 v24, v24, 0x3a800000, v176
	v_rsq_f32_e32 v24, v24
	s_waitcnt vmcnt(8)
	v_pk_mul_f32 v[6:7], v[6:7], v[24:25] op_sel_hi:[1,0]
	v_pk_mul_f32 v[8:9], v[8:9], v[24:25] op_sel_hi:[1,0]
	v_pk_mul_f32 v[12:13], v[12:13], v[24:25] op_sel_hi:[1,0]
	v_pk_mul_f32 v[14:15], v[14:15], v[24:25] op_sel_hi:[1,0]
	v_pk_mul_f32 v[16:17], v[16:17], v[24:25] op_sel_hi:[1,0]
	v_pk_mul_f32 v[18:19], v[18:19], v[24:25] op_sel_hi:[1,0]
	v_pk_mul_f32 v[20:21], v[20:21], v[24:25] op_sel_hi:[1,0]
	v_pk_mul_f32 v[22:23], v[22:23], v[24:25] op_sel_hi:[1,0]
	v_pk_mul_f32 v[6:7], v[6:7], v[40:41]
	v_pk_mul_f32 v[8:9], v[8:9], v[42:43]
	v_pk_mul_f32 v[12:13], v[12:13], v[44:45]
	v_pk_mul_f32 v[14:15], v[14:15], v[46:47]
	v_pk_mul_f32 v[16:17], v[16:17], v[48:49]
	v_pk_mul_f32 v[18:19], v[18:19], v[50:51]
	v_pk_mul_f32 v[20:21], v[20:21], v[52:53]
	v_pk_mul_f32 v[22:23], v[22:23], v[54:55]
	global_store_dwordx4 v[4:5], v[6:9], off offset:-2048
	global_store_dwordx4 v[4:5], v[12:15], off offset:-1024
	global_store_dwordx4 v[4:5], v[16:19], off
	global_store_dwordx4 v[4:5], v[20:23], off offset:1024
	v_lshl_add_u64 v[4:5], v[4:5], 0, s[100:101]
	global_load_dwordx4 v[24:27], v64, s[0:1] offset:-48
	global_load_dwordx4 v[28:31], v64, s[0:1] offset:-32
	global_load_dwordx4 v[32:35], v64, s[0:1] offset:-16
	global_load_dwordx4 v[36:39], v64, s[0:1]
	global_load_dwordx4 v[6:9], v[4:5], off offset:-2048
	global_load_dwordx4 v[12:15], v[4:5], off offset:-1024
	global_load_dwordx4 v[16:19], v[4:5], off
	global_load_dwordx4 v[20:23], v[4:5], off offset:1024
	s_add_u32 s0, s0, 0x10000
	s_addc_u32 s1, s1, 0
	s_waitcnt vmcnt(12)
	v_add_f32_e32 v72, v72, v73
	v_add_f32_e32 v74, v74, v75
	v_add_f32_e32 v76, v76, v77
	v_add_f32_e32 v78, v78, v79
	v_add_f32_e32 v80, v80, v81
	v_add_f32_e32 v82, v82, v83
	v_add_f32_e32 v84, v84, v85
	v_add_f32_e32 v86, v86, v87
	v_add_f32_e32 v72, v72, v74
	v_add_f32_e32 v76, v76, v78
	v_add_f32_e32 v80, v80, v82
	v_add_f32_e32 v84, v84, v86
	v_add_f32_e32 v72, v72, v76
	v_add_f32_e32 v72, v72, v80
	v_add_f32_e32 v72, v72, v84
	v_fmamk_f32 v72, v72, 0x3a800000, v176
	v_rsq_f32_e32 v72, v72
	s_waitcnt vmcnt(8)
	v_pk_mul_f32 v[88:89], v[88:89], v[72:73] op_sel_hi:[1,0]
	v_pk_mul_f32 v[90:91], v[90:91], v[72:73] op_sel_hi:[1,0]
	v_pk_mul_f32 v[92:93], v[92:93], v[72:73] op_sel_hi:[1,0]
	v_pk_mul_f32 v[94:95], v[94:95], v[72:73] op_sel_hi:[1,0]
	v_pk_mul_f32 v[96:97], v[96:97], v[72:73] op_sel_hi:[1,0]
	v_pk_mul_f32 v[98:99], v[98:99], v[72:73] op_sel_hi:[1,0]
	v_pk_mul_f32 v[100:101], v[100:101], v[72:73] op_sel_hi:[1,0]
	v_pk_mul_f32 v[102:103], v[102:103], v[72:73] op_sel_hi:[1,0]
	v_pk_mul_f32 v[88:89], v[88:89], v[40:41]
	v_pk_mul_f32 v[90:91], v[90:91], v[42:43]
	v_pk_mul_f32 v[92:93], v[92:93], v[44:45]
	v_pk_mul_f32 v[94:95], v[94:95], v[46:47]
	v_pk_mul_f32 v[96:97], v[96:97], v[48:49]
	v_pk_mul_f32 v[98:99], v[98:99], v[50:51]
	v_pk_mul_f32 v[100:101], v[100:101], v[52:53]
	v_pk_mul_f32 v[102:103], v[102:103], v[54:55]
	global_store_dwordx4 v[104:105], v[88:91], off offset:-2048
	global_store_dwordx4 v[104:105], v[92:95], off offset:-1024
	global_store_dwordx4 v[104:105], v[96:99], off
	global_store_dwordx4 v[104:105], v[100:103], off offset:1024
	v_lshl_add_u64 v[104:105], v[104:105], 0, s[100:101]
	global_load_dwordx4 v[72:75], v64, s[0:1] offset:-48
	global_load_dwordx4 v[76:79], v64, s[0:1] offset:-32
	global_load_dwordx4 v[80:83], v64, s[0:1] offset:-16
	global_load_dwordx4 v[84:87], v64, s[0:1]
	global_load_dwordx4 v[88:91], v[104:105], off offset:-2048
	global_load_dwordx4 v[92:95], v[104:105], off offset:-1024
	global_load_dwordx4 v[96:99], v[104:105], off
	global_load_dwordx4 v[100:103], v[104:105], off offset:1024
	s_add_u32 s0, s0, 0x10000
	s_addc_u32 s1, s1, 0
	s_waitcnt vmcnt(12)
	v_add_f32_e32 v24, v24, v25
	v_add_f32_e32 v26, v26, v27
	v_add_f32_e32 v28, v28, v29
	v_add_f32_e32 v30, v30, v31
	v_add_f32_e32 v32, v32, v33
	v_add_f32_e32 v34, v34, v35
	v_add_f32_e32 v36, v36, v37
	v_add_f32_e32 v38, v38, v39
	v_add_f32_e32 v24, v24, v26
	v_add_f32_e32 v28, v28, v30
	v_add_f32_e32 v32, v32, v34
	v_add_f32_e32 v36, v36, v38
	v_add_f32_e32 v24, v24, v28
	v_add_f32_e32 v24, v24, v32
	v_add_f32_e32 v24, v24, v36
	v_fmamk_f32 v24, v24, 0x3a800000, v176
	v_rsq_f32_e32 v24, v24
	s_waitcnt vmcnt(8)
	v_pk_mul_f32 v[6:7], v[6:7], v[24:25] op_sel_hi:[1,0]
	v_pk_mul_f32 v[8:9], v[8:9], v[24:25] op_sel_hi:[1,0]
	v_pk_mul_f32 v[12:13], v[12:13], v[24:25] op_sel_hi:[1,0]
	v_pk_mul_f32 v[14:15], v[14:15], v[24:25] op_sel_hi:[1,0]
	v_pk_mul_f32 v[16:17], v[16:17], v[24:25] op_sel_hi:[1,0]
	v_pk_mul_f32 v[18:19], v[18:19], v[24:25] op_sel_hi:[1,0]
	v_pk_mul_f32 v[20:21], v[20:21], v[24:25] op_sel_hi:[1,0]
	v_pk_mul_f32 v[22:23], v[22:23], v[24:25] op_sel_hi:[1,0]
	v_pk_mul_f32 v[6:7], v[6:7], v[40:41]
	v_pk_mul_f32 v[8:9], v[8:9], v[42:43]
	v_pk_mul_f32 v[12:13], v[12:13], v[44:45]
	v_pk_mul_f32 v[14:15], v[14:15], v[46:47]
	v_pk_mul_f32 v[16:17], v[16:17], v[48:49]
	v_pk_mul_f32 v[18:19], v[18:19], v[50:51]
	v_pk_mul_f32 v[20:21], v[20:21], v[52:53]
	v_pk_mul_f32 v[22:23], v[22:23], v[54:55]
	global_store_dwordx4 v[4:5], v[6:9], off offset:-2048
	global_store_dwordx4 v[4:5], v[12:15], off offset:-1024
	global_store_dwordx4 v[4:5], v[16:19], off
	global_store_dwordx4 v[4:5], v[20:23], off offset:1024
	v_lshl_add_u64 v[4:5], v[4:5], 0, s[100:101]
	global_load_dwordx4 v[24:27], v64, s[0:1] offset:-48
	global_load_dwordx4 v[28:31], v64, s[0:1] offset:-32
	global_load_dwordx4 v[32:35], v64, s[0:1] offset:-16
	global_load_dwordx4 v[36:39], v64, s[0:1]
	global_load_dwordx4 v[6:9], v[4:5], off offset:-2048
	global_load_dwordx4 v[12:15], v[4:5], off offset:-1024
	global_load_dwordx4 v[16:19], v[4:5], off
	global_load_dwordx4 v[20:23], v[4:5], off offset:1024
	s_add_u32 s0, s0, 0x10000
	s_addc_u32 s1, s1, 0
	s_waitcnt vmcnt(12)
	v_add_f32_e32 v72, v72, v73
	v_add_f32_e32 v74, v74, v75
	v_add_f32_e32 v76, v76, v77
	v_add_f32_e32 v78, v78, v79
	v_add_f32_e32 v80, v80, v81
	v_add_f32_e32 v82, v82, v83
	v_add_f32_e32 v84, v84, v85
	v_add_f32_e32 v86, v86, v87
	v_add_f32_e32 v72, v72, v74
	v_add_f32_e32 v76, v76, v78
	v_add_f32_e32 v80, v80, v82
	v_add_f32_e32 v84, v84, v86
	v_add_f32_e32 v72, v72, v76
	v_add_f32_e32 v72, v72, v80
	v_add_f32_e32 v72, v72, v84
	v_fmamk_f32 v72, v72, 0x3a800000, v176
	v_rsq_f32_e32 v72, v72
	s_waitcnt vmcnt(8)
	v_pk_mul_f32 v[88:89], v[88:89], v[72:73] op_sel_hi:[1,0]
	v_pk_mul_f32 v[90:91], v[90:91], v[72:73] op_sel_hi:[1,0]
	v_pk_mul_f32 v[92:93], v[92:93], v[72:73] op_sel_hi:[1,0]
	v_pk_mul_f32 v[94:95], v[94:95], v[72:73] op_sel_hi:[1,0]
	v_pk_mul_f32 v[96:97], v[96:97], v[72:73] op_sel_hi:[1,0]
	v_pk_mul_f32 v[98:99], v[98:99], v[72:73] op_sel_hi:[1,0]
	v_pk_mul_f32 v[100:101], v[100:101], v[72:73] op_sel_hi:[1,0]
	v_pk_mul_f32 v[102:103], v[102:103], v[72:73] op_sel_hi:[1,0]
	v_pk_mul_f32 v[88:89], v[88:89], v[40:41]
	v_pk_mul_f32 v[90:91], v[90:91], v[42:43]
	v_pk_mul_f32 v[92:93], v[92:93], v[44:45]
	v_pk_mul_f32 v[94:95], v[94:95], v[46:47]
	v_pk_mul_f32 v[96:97], v[96:97], v[48:49]
	v_pk_mul_f32 v[98:99], v[98:99], v[50:51]
	v_pk_mul_f32 v[100:101], v[100:101], v[52:53]
	v_pk_mul_f32 v[102:103], v[102:103], v[54:55]
	global_store_dwordx4 v[104:105], v[88:91], off offset:-2048
	global_store_dwordx4 v[104:105], v[92:95], off offset:-1024
	global_store_dwordx4 v[104:105], v[96:99], off
	global_store_dwordx4 v[104:105], v[100:103], off offset:1024
	v_lshl_add_u64 v[104:105], v[104:105], 0, s[100:101]
	global_load_dwordx4 v[72:75], v64, s[0:1] offset:-48
	global_load_dwordx4 v[76:79], v64, s[0:1] offset:-32
	global_load_dwordx4 v[80:83], v64, s[0:1] offset:-16
	global_load_dwordx4 v[84:87], v64, s[0:1]
	global_load_dwordx4 v[88:91], v[104:105], off offset:-2048
	global_load_dwordx4 v[92:95], v[104:105], off offset:-1024
	global_load_dwordx4 v[96:99], v[104:105], off
	global_load_dwordx4 v[100:103], v[104:105], off offset:1024
	s_add_u32 s0, s0, 0x10000
	s_addc_u32 s1, s1, 0
	s_waitcnt vmcnt(12)
	v_add_f32_e32 v24, v24, v25
	v_add_f32_e32 v26, v26, v27
	v_add_f32_e32 v28, v28, v29
	v_add_f32_e32 v30, v30, v31
	v_add_f32_e32 v32, v32, v33
	v_add_f32_e32 v34, v34, v35
	v_add_f32_e32 v36, v36, v37
	v_add_f32_e32 v38, v38, v39
	v_add_f32_e32 v24, v24, v26
	v_add_f32_e32 v28, v28, v30
	v_add_f32_e32 v32, v32, v34
	v_add_f32_e32 v36, v36, v38
	v_add_f32_e32 v24, v24, v28
	v_add_f32_e32 v24, v24, v32
	v_add_f32_e32 v24, v24, v36
	v_fmamk_f32 v24, v24, 0x3a800000, v176
	v_rsq_f32_e32 v24, v24
	s_waitcnt vmcnt(8)
	v_pk_mul_f32 v[6:7], v[6:7], v[24:25] op_sel_hi:[1,0]
	v_pk_mul_f32 v[8:9], v[8:9], v[24:25] op_sel_hi:[1,0]
	v_pk_mul_f32 v[12:13], v[12:13], v[24:25] op_sel_hi:[1,0]
	v_pk_mul_f32 v[14:15], v[14:15], v[24:25] op_sel_hi:[1,0]
	v_pk_mul_f32 v[16:17], v[16:17], v[24:25] op_sel_hi:[1,0]
	v_pk_mul_f32 v[18:19], v[18:19], v[24:25] op_sel_hi:[1,0]
	v_pk_mul_f32 v[20:21], v[20:21], v[24:25] op_sel_hi:[1,0]
	v_pk_mul_f32 v[22:23], v[22:23], v[24:25] op_sel_hi:[1,0]
	v_pk_mul_f32 v[6:7], v[6:7], v[40:41]
	v_pk_mul_f32 v[8:9], v[8:9], v[42:43]
	v_pk_mul_f32 v[12:13], v[12:13], v[44:45]
	v_pk_mul_f32 v[14:15], v[14:15], v[46:47]
	v_pk_mul_f32 v[16:17], v[16:17], v[48:49]
	v_pk_mul_f32 v[18:19], v[18:19], v[50:51]
	v_pk_mul_f32 v[20:21], v[20:21], v[52:53]
	v_pk_mul_f32 v[22:23], v[22:23], v[54:55]
	global_store_dwordx4 v[4:5], v[6:9], off offset:-2048
	global_store_dwordx4 v[4:5], v[12:15], off offset:-1024
	global_store_dwordx4 v[4:5], v[16:19], off
	global_store_dwordx4 v[4:5], v[20:23], off offset:1024
	v_lshl_add_u64 v[4:5], v[4:5], 0, s[100:101]
	global_load_dwordx4 v[24:27], v64, s[0:1] offset:-48
	global_load_dwordx4 v[28:31], v64, s[0:1] offset:-32
	global_load_dwordx4 v[32:35], v64, s[0:1] offset:-16
	global_load_dwordx4 v[36:39], v64, s[0:1]
	global_load_dwordx4 v[6:9], v[4:5], off offset:-2048
	global_load_dwordx4 v[12:15], v[4:5], off offset:-1024
	global_load_dwordx4 v[16:19], v[4:5], off
	global_load_dwordx4 v[20:23], v[4:5], off offset:1024
	s_add_u32 s0, s0, 0x10000
	s_addc_u32 s1, s1, 0
	s_waitcnt vmcnt(12)
	v_add_f32_e32 v72, v72, v73
	v_add_f32_e32 v74, v74, v75
	v_add_f32_e32 v76, v76, v77
	v_add_f32_e32 v78, v78, v79
	v_add_f32_e32 v80, v80, v81
	v_add_f32_e32 v82, v82, v83
	v_add_f32_e32 v84, v84, v85
	v_add_f32_e32 v86, v86, v87
	v_add_f32_e32 v72, v72, v74
	v_add_f32_e32 v76, v76, v78
	v_add_f32_e32 v80, v80, v82
	v_add_f32_e32 v84, v84, v86
	v_add_f32_e32 v72, v72, v76
	v_add_f32_e32 v72, v72, v80
	v_add_f32_e32 v72, v72, v84
	v_fmamk_f32 v72, v72, 0x3a800000, v176
	v_rsq_f32_e32 v72, v72
	s_waitcnt vmcnt(8)
	v_pk_mul_f32 v[88:89], v[88:89], v[72:73] op_sel_hi:[1,0]
	v_pk_mul_f32 v[90:91], v[90:91], v[72:73] op_sel_hi:[1,0]
	v_pk_mul_f32 v[92:93], v[92:93], v[72:73] op_sel_hi:[1,0]
	v_pk_mul_f32 v[94:95], v[94:95], v[72:73] op_sel_hi:[1,0]
	v_pk_mul_f32 v[96:97], v[96:97], v[72:73] op_sel_hi:[1,0]
	v_pk_mul_f32 v[98:99], v[98:99], v[72:73] op_sel_hi:[1,0]
	v_pk_mul_f32 v[100:101], v[100:101], v[72:73] op_sel_hi:[1,0]
	v_pk_mul_f32 v[102:103], v[102:103], v[72:73] op_sel_hi:[1,0]
	v_pk_mul_f32 v[88:89], v[88:89], v[40:41]
	v_pk_mul_f32 v[90:91], v[90:91], v[42:43]
	v_pk_mul_f32 v[92:93], v[92:93], v[44:45]
	v_pk_mul_f32 v[94:95], v[94:95], v[46:47]
	v_pk_mul_f32 v[96:97], v[96:97], v[48:49]
	v_pk_mul_f32 v[98:99], v[98:99], v[50:51]
	v_pk_mul_f32 v[100:101], v[100:101], v[52:53]
	v_pk_mul_f32 v[102:103], v[102:103], v[54:55]
	global_store_dwordx4 v[104:105], v[88:91], off offset:-2048
	global_store_dwordx4 v[104:105], v[92:95], off offset:-1024
	global_store_dwordx4 v[104:105], v[96:99], off
	global_store_dwordx4 v[104:105], v[100:103], off offset:1024
	v_lshl_add_u64 v[104:105], v[104:105], 0, s[100:101]
	global_load_dwordx4 v[72:75], v64, s[0:1] offset:-48
	global_load_dwordx4 v[76:79], v64, s[0:1] offset:-32
	global_load_dwordx4 v[80:83], v64, s[0:1] offset:-16
	global_load_dwordx4 v[84:87], v64, s[0:1]
	global_load_dwordx4 v[88:91], v[104:105], off offset:-2048
	global_load_dwordx4 v[92:95], v[104:105], off offset:-1024
	global_load_dwordx4 v[96:99], v[104:105], off
	global_load_dwordx4 v[100:103], v[104:105], off offset:1024
	s_add_u32 s0, s0, 0x10000
	s_addc_u32 s1, s1, 0
	s_waitcnt vmcnt(12)
	v_add_f32_e32 v24, v24, v25
	v_add_f32_e32 v26, v26, v27
	v_add_f32_e32 v28, v28, v29
	v_add_f32_e32 v30, v30, v31
	v_add_f32_e32 v32, v32, v33
	v_add_f32_e32 v34, v34, v35
	v_add_f32_e32 v36, v36, v37
	v_add_f32_e32 v38, v38, v39
	v_add_f32_e32 v24, v24, v26
	v_add_f32_e32 v28, v28, v30
	v_add_f32_e32 v32, v32, v34
	v_add_f32_e32 v36, v36, v38
	v_add_f32_e32 v24, v24, v28
	v_add_f32_e32 v24, v24, v32
	v_add_f32_e32 v24, v24, v36
	v_fmamk_f32 v24, v24, 0x3a800000, v176
	v_rsq_f32_e32 v24, v24
	s_waitcnt vmcnt(8)
	v_pk_mul_f32 v[6:7], v[6:7], v[24:25] op_sel_hi:[1,0]
	v_pk_mul_f32 v[8:9], v[8:9], v[24:25] op_sel_hi:[1,0]
	v_pk_mul_f32 v[12:13], v[12:13], v[24:25] op_sel_hi:[1,0]
	v_pk_mul_f32 v[14:15], v[14:15], v[24:25] op_sel_hi:[1,0]
	v_pk_mul_f32 v[16:17], v[16:17], v[24:25] op_sel_hi:[1,0]
	v_pk_mul_f32 v[18:19], v[18:19], v[24:25] op_sel_hi:[1,0]
	v_pk_mul_f32 v[20:21], v[20:21], v[24:25] op_sel_hi:[1,0]
	v_pk_mul_f32 v[22:23], v[22:23], v[24:25] op_sel_hi:[1,0]
	v_pk_mul_f32 v[6:7], v[6:7], v[40:41]
	v_pk_mul_f32 v[8:9], v[8:9], v[42:43]
	v_pk_mul_f32 v[12:13], v[12:13], v[44:45]
	v_pk_mul_f32 v[14:15], v[14:15], v[46:47]
	v_pk_mul_f32 v[16:17], v[16:17], v[48:49]
	v_pk_mul_f32 v[18:19], v[18:19], v[50:51]
	v_pk_mul_f32 v[20:21], v[20:21], v[52:53]
	v_pk_mul_f32 v[22:23], v[22:23], v[54:55]
	global_store_dwordx4 v[4:5], v[6:9], off offset:-2048
	global_store_dwordx4 v[4:5], v[12:15], off offset:-1024
	global_store_dwordx4 v[4:5], v[16:19], off
	global_store_dwordx4 v[4:5], v[20:23], off offset:1024
	v_lshl_add_u64 v[4:5], v[4:5], 0, s[100:101]
	global_load_dwordx4 v[24:27], v64, s[0:1] offset:-48
	global_load_dwordx4 v[28:31], v64, s[0:1] offset:-32
	global_load_dwordx4 v[32:35], v64, s[0:1] offset:-16
	global_load_dwordx4 v[36:39], v64, s[0:1]
	global_load_dwordx4 v[6:9], v[4:5], off offset:-2048
	global_load_dwordx4 v[12:15], v[4:5], off offset:-1024
	global_load_dwordx4 v[16:19], v[4:5], off
	global_load_dwordx4 v[20:23], v[4:5], off offset:1024
	s_add_u32 s0, s0, 0x10000
	s_addc_u32 s1, s1, 0
	s_waitcnt vmcnt(12)
	v_add_f32_e32 v72, v72, v73
	v_add_f32_e32 v74, v74, v75
	v_add_f32_e32 v76, v76, v77
	v_add_f32_e32 v78, v78, v79
	v_add_f32_e32 v80, v80, v81
	v_add_f32_e32 v82, v82, v83
	v_add_f32_e32 v84, v84, v85
	v_add_f32_e32 v86, v86, v87
	v_add_f32_e32 v72, v72, v74
	v_add_f32_e32 v76, v76, v78
	v_add_f32_e32 v80, v80, v82
	v_add_f32_e32 v84, v84, v86
	v_add_f32_e32 v72, v72, v76
	v_add_f32_e32 v72, v72, v80
	v_add_f32_e32 v72, v72, v84
	v_fmamk_f32 v72, v72, 0x3a800000, v176
	v_rsq_f32_e32 v72, v72
	s_waitcnt vmcnt(8)
	v_pk_mul_f32 v[88:89], v[88:89], v[72:73] op_sel_hi:[1,0]
	v_pk_mul_f32 v[90:91], v[90:91], v[72:73] op_sel_hi:[1,0]
	v_pk_mul_f32 v[92:93], v[92:93], v[72:73] op_sel_hi:[1,0]
	v_pk_mul_f32 v[94:95], v[94:95], v[72:73] op_sel_hi:[1,0]
	v_pk_mul_f32 v[96:97], v[96:97], v[72:73] op_sel_hi:[1,0]
	v_pk_mul_f32 v[98:99], v[98:99], v[72:73] op_sel_hi:[1,0]
	v_pk_mul_f32 v[100:101], v[100:101], v[72:73] op_sel_hi:[1,0]
	v_pk_mul_f32 v[102:103], v[102:103], v[72:73] op_sel_hi:[1,0]
	v_pk_mul_f32 v[88:89], v[88:89], v[40:41]
	v_pk_mul_f32 v[90:91], v[90:91], v[42:43]
	v_pk_mul_f32 v[92:93], v[92:93], v[44:45]
	v_pk_mul_f32 v[94:95], v[94:95], v[46:47]
	v_pk_mul_f32 v[96:97], v[96:97], v[48:49]
	v_pk_mul_f32 v[98:99], v[98:99], v[50:51]
	v_pk_mul_f32 v[100:101], v[100:101], v[52:53]
	v_pk_mul_f32 v[102:103], v[102:103], v[54:55]
	global_store_dwordx4 v[104:105], v[88:91], off offset:-2048
	global_store_dwordx4 v[104:105], v[92:95], off offset:-1024
	global_store_dwordx4 v[104:105], v[96:99], off
	global_store_dwordx4 v[104:105], v[100:103], off offset:1024
	v_lshl_add_u64 v[104:105], v[104:105], 0, s[100:101]
	global_load_dwordx4 v[72:75], v64, s[0:1] offset:-48
	global_load_dwordx4 v[76:79], v64, s[0:1] offset:-32
	global_load_dwordx4 v[80:83], v64, s[0:1] offset:-16
	global_load_dwordx4 v[84:87], v64, s[0:1]
	global_load_dwordx4 v[88:91], v[104:105], off offset:-2048
	global_load_dwordx4 v[92:95], v[104:105], off offset:-1024
	global_load_dwordx4 v[96:99], v[104:105], off
	global_load_dwordx4 v[100:103], v[104:105], off offset:1024
	s_add_u32 s0, s0, 0x10000
	s_addc_u32 s1, s1, 0
	s_waitcnt vmcnt(12)
	v_add_f32_e32 v24, v24, v25
	v_add_f32_e32 v26, v26, v27
	v_add_f32_e32 v28, v28, v29
	v_add_f32_e32 v30, v30, v31
	v_add_f32_e32 v32, v32, v33
	v_add_f32_e32 v34, v34, v35
	v_add_f32_e32 v36, v36, v37
	v_add_f32_e32 v38, v38, v39
	v_add_f32_e32 v24, v24, v26
	v_add_f32_e32 v28, v28, v30
	v_add_f32_e32 v32, v32, v34
	v_add_f32_e32 v36, v36, v38
	v_add_f32_e32 v24, v24, v28
	v_add_f32_e32 v24, v24, v32
	v_add_f32_e32 v24, v24, v36
	v_fmamk_f32 v24, v24, 0x3a800000, v176
	v_rsq_f32_e32 v24, v24
	s_waitcnt vmcnt(8)
	v_pk_mul_f32 v[6:7], v[6:7], v[24:25] op_sel_hi:[1,0]
	v_pk_mul_f32 v[8:9], v[8:9], v[24:25] op_sel_hi:[1,0]
	v_pk_mul_f32 v[12:13], v[12:13], v[24:25] op_sel_hi:[1,0]
	v_pk_mul_f32 v[14:15], v[14:15], v[24:25] op_sel_hi:[1,0]
	v_pk_mul_f32 v[16:17], v[16:17], v[24:25] op_sel_hi:[1,0]
	v_pk_mul_f32 v[18:19], v[18:19], v[24:25] op_sel_hi:[1,0]
	v_pk_mul_f32 v[20:21], v[20:21], v[24:25] op_sel_hi:[1,0]
	v_pk_mul_f32 v[22:23], v[22:23], v[24:25] op_sel_hi:[1,0]
	v_pk_mul_f32 v[6:7], v[6:7], v[40:41]
	v_pk_mul_f32 v[8:9], v[8:9], v[42:43]
	v_pk_mul_f32 v[12:13], v[12:13], v[44:45]
	v_pk_mul_f32 v[14:15], v[14:15], v[46:47]
	v_pk_mul_f32 v[16:17], v[16:17], v[48:49]
	v_pk_mul_f32 v[18:19], v[18:19], v[50:51]
	v_pk_mul_f32 v[20:21], v[20:21], v[52:53]
	v_pk_mul_f32 v[22:23], v[22:23], v[54:55]
	global_store_dwordx4 v[4:5], v[6:9], off offset:-2048
	global_store_dwordx4 v[4:5], v[12:15], off offset:-1024
	global_store_dwordx4 v[4:5], v[16:19], off
	global_store_dwordx4 v[4:5], v[20:23], off offset:1024
	v_lshl_add_u64 v[4:5], v[4:5], 0, s[100:101]
	s_waitcnt vmcnt(4)
	v_add_f32_e32 v72, v72, v73
	v_add_f32_e32 v74, v74, v75
	v_add_f32_e32 v76, v76, v77
	v_add_f32_e32 v78, v78, v79
	v_add_f32_e32 v80, v80, v81
	v_add_f32_e32 v82, v82, v83
	v_add_f32_e32 v84, v84, v85
	v_add_f32_e32 v86, v86, v87
	v_add_f32_e32 v72, v72, v74
	v_add_f32_e32 v76, v76, v78
	v_add_f32_e32 v80, v80, v82
	v_add_f32_e32 v84, v84, v86
	v_add_f32_e32 v72, v72, v76
	v_add_f32_e32 v72, v72, v80
	v_add_f32_e32 v72, v72, v84
	v_fmamk_f32 v72, v72, 0x3a800000, v176
	v_rsq_f32_e32 v72, v72
	s_waitcnt vmcnt(0)
	v_pk_mul_f32 v[88:89], v[88:89], v[72:73] op_sel_hi:[1,0]
	v_pk_mul_f32 v[90:91], v[90:91], v[72:73] op_sel_hi:[1,0]
	v_pk_mul_f32 v[92:93], v[92:93], v[72:73] op_sel_hi:[1,0]
	v_pk_mul_f32 v[94:95], v[94:95], v[72:73] op_sel_hi:[1,0]
	v_pk_mul_f32 v[96:97], v[96:97], v[72:73] op_sel_hi:[1,0]
	v_pk_mul_f32 v[98:99], v[98:99], v[72:73] op_sel_hi:[1,0]
	v_pk_mul_f32 v[100:101], v[100:101], v[72:73] op_sel_hi:[1,0]
	v_pk_mul_f32 v[102:103], v[102:103], v[72:73] op_sel_hi:[1,0]
	v_pk_mul_f32 v[88:89], v[88:89], v[40:41]
	v_pk_mul_f32 v[90:91], v[90:91], v[42:43]
	v_pk_mul_f32 v[92:93], v[92:93], v[44:45]
	v_pk_mul_f32 v[94:95], v[94:95], v[46:47]
	v_pk_mul_f32 v[96:97], v[96:97], v[48:49]
	v_pk_mul_f32 v[98:99], v[98:99], v[50:51]
	v_pk_mul_f32 v[100:101], v[100:101], v[52:53]
	v_pk_mul_f32 v[102:103], v[102:103], v[54:55]
	global_store_dwordx4 v[104:105], v[88:91], off offset:-2048
	global_store_dwordx4 v[104:105], v[92:95], off offset:-1024
	global_store_dwordx4 v[104:105], v[96:99], off
	global_store_dwordx4 v[104:105], v[100:103], off offset:1024
	v_lshl_add_u64 v[104:105], v[104:105], 0, s[100:101]
